# P0 row phase: the four gain-vector pieces loaded together with the row (3 dependent round trips per row removed)
# baseline (speedup 1.0000x reference)
; DI unsigned pk2(float lo, float hi) { f32x2 v = {lo, hi}; bf16x2_t b = __builtin_convertvector(v, bf16x2_t); return __builtin_bit_cast(unsigned, b); }
; DI float bflo(unsigned u) { return __uint_as_float(u << 16); }
; DI float bfhi(unsigned u) { return __uint_as_float(u & 0xffff0000u); }
; DI void st16_wt(void* p, u32x4 v) { asm volatile("global_store_dwordx4 %0, %1, off sc0 sc1\n\ts_nop 1" :: "v"(p), "v"(v) : "memory"); }
; DI void row_phase(int wv, int mode, const float* X, const bf16_t* Y, const float* ga, float coef, const float* gb, float* Xout, bf16_t* A, int a_pad) {
;     ...
;     for (int r = gw; r < MTOK; r += NGW) {
;         f32x4 v[4];
; #pragma unroll
;         for (int j = 0; j < 4; ++j) v[j] = *(const f32x4*)(X + (size_t)r * DM + 4 * lane + 256 * j);
;         if (mode == 1) { f32x4 y[4]; float s = 0.f;
; #pragma unroll
;             for (int j = 0; j < 4; ++j) { const u32x2 yv = *(const u32x2*)(Y + (size_t)r * DM + 4 * lane + 256 * j); y[j] = (f32x4){bflo(yv.x), bfhi(yv.x), bflo(yv.y), bfhi(yv.y)}; s += y[j][0] * y[j][0] + y[j][1] * y[j][1] + y[j][2] * y[j][2] + y[j][3] * y[j][3]; }
;             const float rs = coef * rsqrtf(wave_sum(s) * (1.f / DM) + 1e-6f);
; #pragma unroll
;             for (int j = 0; j < 4; ++j) { const f32x4 gg = *(const f32x4*)(ga + 4 * lane + 256 * j); v[j] += y[j] * gg * rs; } }
;         if (Xout) {
; #pragma unroll
;             for (int j = 0; j < 4; ++j) st16_wt(Xout + (size_t)r * DM + 4 * lane + 256 * j, __builtin_bit_cast(u32x4, v[j])); }
;         if (gb) { float s = 0.f;
; #pragma unroll
;             for (int j = 0; j < 4; ++j) s += v[j][0] * v[j][0] + v[j][1] * v[j][1] + v[j][2] * v[j][2] + v[j][3] * v[j][3];
;             const float rs = rsqrtf(wave_sum(s) * (1.f / DM) + 1e-6f);
;             const size_t ar = a_pad ? (size_t)(r + (r >> 13) + 1) : (size_t)r;
; #pragma unroll
;             for (int j = 0; j < 4; ++j) { const f32x4 gg = *(const f32x4*)(gb + 4 * lane + 256 * j); const f32x4 o = v[j] * gg * rs;
;                 u32x2 w; w.x = pk2(o[0], o[1]); w.y = pk2(o[2], o[3]); *(u32x2*)(A + ar * DM + 4 * lane + 256 * j) = w; } }
.LBB0_321:
	s_and_b64 vcc, exec, s[2:3]
	s_cbranch_vccnz .LBB0_320
	global_load_dwordx4 v[8:11], v[6:7], off offset:-3072
	global_load_dwordx4 v[12:15], v[6:7], off offset:-2048
	global_load_dwordx4 v[16:19], v[6:7], off offset:-1024
	global_load_dwordx4 v[20:23], v[6:7], off
	global_load_dwordx4 v[24:27], v[0:1], off
	global_load_dwordx4 v[96:99], v[0:1], off offset:1024
	global_load_dwordx4 v[100:103], v[0:1], off offset:2048
	global_load_dwordx4 v[104:107], v[0:1], off offset:3072
	s_waitcnt vmcnt(0)
	v_mul_f32_e32 v28, v9, v9
	v_mul_f32_e32 v29, v13, v13
	v_mul_f32_e32 v30, v17, v17
	v_fmac_f32_e32 v28, v8, v8
	v_fmac_f32_e32 v29, v12, v12
	v_mul_f32_e32 v31, v21, v21
	v_fmac_f32_e32 v30, v16, v16
	v_fmac_f32_e32 v28, v10, v10
	v_fmac_f32_e32 v29, v14, v14
	v_fmac_f32_e32 v31, v20, v20
	v_fmac_f32_e32 v30, v18, v18
	v_fmac_f32_e32 v28, v11, v11
	v_fmac_f32_e32 v29, v15, v15
	v_fmac_f32_e32 v31, v22, v22
	v_fmac_f32_e32 v30, v19, v19
	v_add_f32_e32 v28, v28, v29
	v_fmac_f32_e32 v31, v23, v23
	v_add_f32_e32 v28, v28, v30
	v_add_f32_e32 v28, v28, v31
	v_pk_mul_f32 v[8:9], v[8:9], v[24:25]
	v_pk_mul_f32 v[10:11], v[10:11], v[26:27]
	v_add_f32_dpp v28, v28, v28 quad_perm:[1,0,3,2] row_mask:0xf bank_mask:0xf bound_ctrl:1
	s_nop 1
	v_add_f32_dpp v28, v28, v28 quad_perm:[2,3,0,1] row_mask:0xf bank_mask:0xf bound_ctrl:1
	s_nop 1
	v_add_f32_dpp v28, v28, v28 row_half_mirror row_mask:0xf bank_mask:0xf bound_ctrl:1
	s_nop 1
	v_add_f32_dpp v28, v28, v28 row_mirror row_mask:0xf bank_mask:0xf bound_ctrl:1
	v_mov_b32_e32 v29, v28
	s_nop 1
	v_permlane16_swap_b32_e32 v28, v29
	v_add_f32_e32 v28, v28, v29
	v_mov_b32_e32 v29, v28
	s_nop 1
	v_permlane32_swap_b32_e32 v28, v29
	v_add_f32_e32 v28, v28, v29
	v_fmamk_f32 v28, v28, 0x3a800000, v3
	v_mul_f32_e32 v29, 0x4b800000, v28
	v_cmp_gt_f32_e32 vcc, s11, v28
	s_nop 1
	v_cndmask_b32_e32 v28, v28, v29, vcc
	v_rsq_f32_e32 v28, v28
	s_nop 0
	v_mul_f32_e32 v24, 0x45800000, v28
	v_cndmask_b32_e32 v24, v28, v24, vcc
	v_pk_mul_f32 v[10:11], v[10:11], v[24:25] op_sel_hi:[1,0]
	v_pk_mul_f32 v[8:9], v[8:9], v[24:25] op_sel_hi:[1,0]
	s_nop 0
	v_cvt_pk_bf16_f32 v8, v8, v9
	v_cvt_pk_bf16_f32 v9, v10, v11
	flat_store_dwordx2 v[4:5], v[8:9]
	v_pk_mul_f32 v[10:11], v[14:15], v[98:99]
	v_pk_mul_f32 v[8:9], v[12:13], v[96:97]
	v_pk_mul_f32 v[10:11], v[10:11], v[24:25] op_sel_hi:[1,0]
	v_pk_mul_f32 v[8:9], v[8:9], v[24:25] op_sel_hi:[1,0]
	s_nop 0
	v_cvt_pk_bf16_f32 v8, v8, v9
	v_cvt_pk_bf16_f32 v9, v10, v11
	flat_store_dwordx2 v[4:5], v[8:9] offset:512
	v_pk_mul_f32 v[10:11], v[18:19], v[102:103]
	v_pk_mul_f32 v[8:9], v[16:17], v[100:101]
	v_pk_mul_f32 v[10:11], v[10:11], v[24:25] op_sel_hi:[1,0]
	v_pk_mul_f32 v[8:9], v[8:9], v[24:25] op_sel_hi:[1,0]
	s_nop 0
	v_cvt_pk_bf16_f32 v8, v8, v9
	v_cvt_pk_bf16_f32 v9, v10, v11
	flat_store_dwordx2 v[4:5], v[8:9] offset:1024
	v_pk_mul_f32 v[10:11], v[22:23], v[106:107]
	v_pk_mul_f32 v[8:9], v[20:21], v[104:105]
	v_pk_mul_f32 v[10:11], v[10:11], v[24:25] op_sel_hi:[1,0]
	v_pk_mul_f32 v[8:9], v[8:9], v[24:25] op_sel_hi:[1,0]
	s_nop 0
	v_cvt_pk_bf16_f32 v8, v8, v9
	v_cvt_pk_bf16_f32 v9, v10, v11
	flat_store_dwordx2 v[4:5], v[8:9] offset:1536
	s_branch .LBB0_320
